# grid barrier: non-leader workgroups poll the cross-XCD generation word directly instead of waiting for the per-XCD relay
# speedup vs baseline: 1.0111x; 1.0111x over previous
.Lgs_102:
	s_or_b64 exec, exec, s[8:9]
	v_cvt_f32_u32_e32 v4, v2
	s_waitcnt vmcnt(0)
	v_readfirstlane_b32 s8, v3
	v_sub_u32_e32 v3, 0, v2
	v_rcp_iflag_f32_e32 v4, v4
	v_add_u32_e32 v5, s8, v1
	v_mul_f32_e32 v4, 0x4f7ffffe, v4
	v_cvt_u32_f32_e32 v4, v4
	v_mul_lo_u32 v1, v3, v4
	v_mul_hi_u32 v1, v4, v1
	v_add_u32_e32 v1, v4, v1
	v_mul_hi_u32 v1, v5, v1
	v_mul_lo_u32 v3, v1, v2
	v_sub_u32_e32 v3, v5, v3
	v_add_u32_e32 v4, 1, v1
	v_sub_u32_e32 v6, v3, v2
	v_cmp_ge_u32_e32 vcc, v3, v2
	s_nop 1
	v_cndmask_b32_e32 v1, v1, v4, vcc
	v_cndmask_b32_e32 v3, v3, v6, vcc
	v_add_u32_e32 v4, 1, v1
	v_cmp_ge_u32_e32 vcc, v3, v2
	v_add_u32_e32 v3, 1, v5
	s_nop 0
	v_cndmask_b32_e32 v1, v1, v4, vcc
	v_mul_lo_u32 v4, v2, v1
	v_add_u32_e32 v2, v4, v2
	v_cmp_ne_u32_e32 vcc, v3, v2
	s_and_saveexec_b64 s[8:9], vcc
	s_xor_b64 s[8:9], exec, s[8:9]
	s_cbranch_execz .Lgs_116
	v_readlane_b32 s10, v250, 49
	v_readlane_b32 s11, v250, 50
	s_waitcnt lgkmcnt(0)
	s_nop 3
	global_load_dword v0, v157, s[10:11] sc1
	s_waitcnt vmcnt(0)
	v_cmp_eq_u32_e32 vcc, v0, v1
	s_and_saveexec_b64 s[10:11], vcc
	s_cbranch_execz .Lgs_115
	s_mov_b64 s[46:47], s[22:23]
	s_mov_b32 s40, 1
	s_mov_b64 s[12:13], 0
	s_branch .Lgs_106

.Lgs_110:
	v_readlane_b32 s16, v250, 49
	v_readlane_b32 s17, v250, 50
	s_add_i32 s40, s40, 1
	s_mov_b64 s[18:19], -1
	s_nop 2
	global_load_dword v0, v157, s[16:17] sc1
	s_waitcnt vmcnt(0)
	v_cmp_ne_u32_e32 vcc, v0, v1
	s_orn2_b64 s[16:17], vcc, exec
	s_branch .Lgs_105

.LBB0_170:
	s_or_b64 exec, exec, s[4:5]
	v_cvt_f32_u32_e32 v4, v2
	s_waitcnt vmcnt(0)
	v_readfirstlane_b32 s4, v3
	v_sub_u32_e32 v3, 0, v2
	v_rcp_iflag_f32_e32 v4, v4
	v_add_u32_e32 v5, s4, v1
	v_mul_f32_e32 v4, 0x4f7ffffe, v4
	v_cvt_u32_f32_e32 v4, v4
	v_mul_lo_u32 v1, v3, v4
	v_mul_hi_u32 v1, v4, v1
	v_add_u32_e32 v1, v4, v1
	v_mul_hi_u32 v1, v5, v1
	v_mul_lo_u32 v3, v1, v2
	v_sub_u32_e32 v3, v5, v3
	v_add_u32_e32 v4, 1, v1
	v_cmp_ge_u32_e32 vcc, v3, v2
	s_nop 1
	v_cndmask_b32_e32 v1, v1, v4, vcc
	v_sub_u32_e32 v4, v3, v2
	v_cndmask_b32_e32 v3, v3, v4, vcc
	v_add_u32_e32 v4, 1, v1
	v_cmp_ge_u32_e32 vcc, v3, v2
	v_add_u32_e32 v3, 1, v5
	s_nop 0
	v_cndmask_b32_e32 v1, v1, v4, vcc
	v_mul_lo_u32 v4, v2, v1
	v_add_u32_e32 v2, v4, v2
	v_cmp_ne_u32_e32 vcc, v3, v2
	s_and_saveexec_b64 s[4:5], vcc
	s_xor_b64 s[4:5], exec, s[4:5]
	s_cbranch_execz .LBB0_184
	v_readlane_b32 s8, v250, 49
	v_readlane_b32 s9, v250, 50
	s_waitcnt lgkmcnt(0)
	s_nop 3
	global_load_dword v0, v157, s[8:9] sc1
	s_waitcnt vmcnt(0)
	v_cmp_eq_u32_e32 vcc, v0, v1
	s_and_saveexec_b64 s[8:9], vcc
	s_cbranch_execz .LBB0_183
	s_mov_b64 s[40:41], s[22:23]
	s_mov_b32 s22, 1
	s_mov_b64 s[10:11], 0
	s_branch .LBB0_174

.LBB0_178:
	v_readlane_b32 s14, v250, 49
	v_readlane_b32 s15, v250, 50
	s_add_i32 s22, s22, 1
	s_mov_b64 s[16:17], -1
	s_nop 2
	global_load_dword v0, v157, s[14:15] sc1
	s_waitcnt vmcnt(0)
	v_cmp_ne_u32_e32 vcc, v0, v1
	s_orn2_b64 s[14:15], vcc, exec
	s_branch .LBB0_173

.LBB0_246:
	s_or_b64 exec, exec, s[4:5]
	v_cvt_f32_u32_e32 v4, v2
	s_waitcnt vmcnt(0)
	v_readfirstlane_b32 s4, v3
	v_sub_u32_e32 v3, 0, v2
	v_rcp_iflag_f32_e32 v4, v4
	v_add_u32_e32 v5, s4, v1
	v_mul_f32_e32 v4, 0x4f7ffffe, v4
	v_cvt_u32_f32_e32 v4, v4
	v_mul_lo_u32 v1, v3, v4
	v_mul_hi_u32 v1, v4, v1
	v_add_u32_e32 v1, v4, v1
	v_mul_hi_u32 v1, v5, v1
	v_mul_lo_u32 v3, v1, v2
	v_sub_u32_e32 v3, v5, v3
	v_add_u32_e32 v4, 1, v1
	v_cmp_ge_u32_e32 vcc, v3, v2
	s_nop 1
	v_cndmask_b32_e32 v1, v1, v4, vcc
	v_sub_u32_e32 v4, v3, v2
	v_cndmask_b32_e32 v3, v3, v4, vcc
	v_add_u32_e32 v4, 1, v1
	v_cmp_ge_u32_e32 vcc, v3, v2
	v_add_u32_e32 v3, 1, v5
	s_nop 0
	v_cndmask_b32_e32 v1, v1, v4, vcc
	v_mul_lo_u32 v4, v2, v1
	v_add_u32_e32 v2, v4, v2
	v_cmp_ne_u32_e32 vcc, v3, v2
	s_and_saveexec_b64 s[4:5], vcc
	s_xor_b64 s[4:5], exec, s[4:5]
	s_cbranch_execz .LBB0_260
	v_readlane_b32 s6, v250, 49
	v_readlane_b32 s7, v250, 50
	s_waitcnt lgkmcnt(0)
	s_nop 3
	global_load_dword v0, v157, s[6:7] sc1
	s_waitcnt vmcnt(0)
	v_cmp_eq_u32_e32 vcc, v0, v1
	s_and_saveexec_b64 s[6:7], vcc
	s_cbranch_execz .LBB0_259
	s_mov_b32 s18, 1
	s_mov_b64 s[8:9], 0
	s_branch .LBB0_250

.LBB0_254:
	v_readlane_b32 s12, v250, 49
	v_readlane_b32 s13, v250, 50
	s_add_i32 s18, s18, 1
	s_mov_b64 s[14:15], -1
	s_nop 2
	global_load_dword v0, v157, s[12:13] sc1
	s_waitcnt vmcnt(0)
	v_cmp_ne_u32_e32 vcc, v0, v1
	s_orn2_b64 s[12:13], vcc, exec
	s_branch .LBB0_249
